# grid barrier spin loops without s_sleep between polls
# speedup vs baseline: 1.0019x; 1.0019x over previous
; __device__ __forceinline__ unsigned xb_ld(unsigned* p)              { return __hip_atomic_load(p, __ATOMIC_RELAXED, __HIP_MEMORY_SCOPE_AGENT); }
; __device__ __forceinline__ void xcd_barrier_complete(unsigned* bar, unsigned x, unsigned& nloc, unsigned& nx) {
;     ...
;     for (;;) {
;         sum = 0u; cnt = 0u; mine = 0u;
; #pragma unroll
;         for (unsigned j = 0; j < 16; ++j) { const unsigned c = xb_ld(&bar[XB_XCNT(j)]); sum += c; cnt += (c > 0u) ? 1u : 0u; mine = (j == x) ? c : mine; }
;         if (sum == G) break;
;         __builtin_amdgcn_s_sleep(1);
;         if ((++sp & 255u) == 0u) { if (xb_ld(&bar[XB_TMO])) break; if (sp > XB_SPIN_CAP) { atomicAdd(&bar[XB_TMO], 1u); break; } }
;     }
.LBB0_519:
	global_load_dword v16, v1, s[10:11] sc1
	s_waitcnt lgkmcnt(0)
	global_load_dword v0, v1, s[12:13] sc1
	global_load_dword v2, v1, s[14:15] sc1
	global_load_dword v3, v1, s[16:17] sc1
	global_load_dword v4, v1, s[18:19] sc1
	global_load_dword v5, v1, s[20:21] sc1
	global_load_dword v6, v1, s[22:23] sc1
	global_load_dword v7, v1, s[24:25] sc1
	global_load_dword v8, v1, s[26:27] sc1
	global_load_dword v9, v1, s[28:29] sc1
	global_load_dword v10, v1, s[30:31] sc1
	global_load_dword v11, v1, s[34:35] sc1
	global_load_dword v12, v1, s[36:37] sc1
	global_load_dword v13, v1, s[38:39] sc1
	global_load_dword v14, v1, s[40:41] sc1
	global_load_dword v15, v1, s[42:43] sc1
	s_mov_b64 s[44:45], -1
	s_mov_b64 s[46:47], -1
	s_waitcnt vmcnt(14)
	v_add_u32_e32 v17, v0, v16
	s_waitcnt vmcnt(13)
	v_add_u32_e32 v17, v17, v2
	s_waitcnt vmcnt(12)
	v_add_u32_e32 v17, v17, v3
	s_waitcnt vmcnt(11)
	v_add_u32_e32 v17, v17, v4
	s_waitcnt vmcnt(10)
	v_add_u32_e32 v17, v17, v5
	s_waitcnt vmcnt(9)
	v_add_u32_e32 v17, v17, v6
	s_waitcnt vmcnt(8)
	v_add_u32_e32 v17, v17, v7
	s_waitcnt vmcnt(7)
	v_add_u32_e32 v17, v17, v8
	s_waitcnt vmcnt(6)
	v_add_u32_e32 v17, v17, v9
	s_waitcnt vmcnt(5)
	v_add_u32_e32 v17, v17, v10
	s_waitcnt vmcnt(4)
	v_add_u32_e32 v17, v17, v11
	s_waitcnt vmcnt(3)
	v_add_u32_e32 v17, v17, v12
	s_waitcnt vmcnt(2)
	v_add_u32_e32 v17, v17, v13
	s_waitcnt vmcnt(1)
	v_add_u32_e32 v17, v17, v14
	s_waitcnt vmcnt(0)
	v_add_u32_e32 v17, v17, v15
	v_cmp_eq_u32_e32 vcc, s85, v17
	s_cbranch_vccnz .LBB0_518
	s_and_b32 s44, s50, 0xff
	s_cmp_eq_u32 s44, 0
	s_mov_b64 s[44:45], -1
	s_mov_b64 s[48:49], -1
	s_cbranch_scc1 .LBB0_523
	s_and_b64 vcc, exec, s[48:49]
	s_cbranch_vccz .LBB0_518

; __device__ __forceinline__ unsigned xb_ld(unsigned* p)              { return __hip_atomic_load(p, __ATOMIC_RELAXED, __HIP_MEMORY_SCOPE_AGENT); }
; #define XB_SPIN(cond, bar) do { unsigned _sp = 0; while (cond) { __builtin_amdgcn_s_sleep(1); \
;     if ((++_sp & 255u) == 0u) { if (xb_ld(&(bar)[XB_TMO])) break; if (_sp > XB_SPIN_CAP) { atomicAdd(&(bar)[XB_TMO], 1u); break; } } } } while (0)
; __device__ __forceinline__ void xcd_barrier(const XcdBarrier& b) {
;     ...
;             else XB_SPIN(xb_ld(&bar[XB_TOPGEN]) == tg, bar);
.LBB0_537:
	s_and_b32 s24, s2, 0xff
	s_mov_b64 s[22:23], -1
	s_cmp_lg_u32 s24, 0
	s_mov_b64 s[26:27], -1
	s_cbranch_scc0 .LBB0_540
	s_and_b64 vcc, exec, s[26:27]
	s_cbranch_vccz .LBB0_536

; __device__ __forceinline__ unsigned xb_ld(unsigned* p)              { return __hip_atomic_load(p, __ATOMIC_RELAXED, __HIP_MEMORY_SCOPE_AGENT); }
; #define XB_SPIN(cond, bar) do { unsigned _sp = 0; while (cond) { __builtin_amdgcn_s_sleep(1); \
;     if ((++_sp & 255u) == 0u) { if (xb_ld(&(bar)[XB_TMO])) break; if (_sp > XB_SPIN_CAP) { atomicAdd(&(bar)[XB_TMO], 1u); break; } } } } while (0)
; __device__ __forceinline__ void xcd_barrier(const XcdBarrier& b) {
;     ...
;             XB_SPIN(xb_ld(&bar[XB_XGEN(b.x)]) == gen, bar);
.LBB0_554:
	s_and_b32 s22, s2, 0xff
	s_mov_b64 s[20:21], -1
	s_cmp_lg_u32 s22, 0
	s_mov_b64 s[24:25], -1
	s_cbranch_scc0 .LBB0_557
	s_and_b64 vcc, exec, s[24:25]
	s_cbranch_vccz .LBB0_553

; __global__ void __launch_bounds__(512, 2) mega_fwd(Args ka) {
;     ...
;         if (ph_hi > 100000) grid.sync();
.LBB0_577:
	global_load_dword v2, v1, s[6:7] offset:32 sc1
	s_waitcnt vmcnt(0)
	v_and_b32_e32 v2, 0xffff0000, v2
	v_cmp_ne_u32_e32 vcc, v2, v0
	s_or_b64 s[8:9], vcc, s[8:9]
	s_andn2_b64 exec, exec, s[8:9]
	s_cbranch_execnz .LBB0_577
	s_branch .LBB0_19
